# prep gate vectors split across waves 0 and 1 (forward/backward direction each computed by one wave with the same code) + compute-dtype comment
# speedup vs baseline: 1.0051x; 1.0032x over previous
.LBB0_362:
	s_or_b64 exec, exec, s[2:3]
	v_mul_f32_e32 v0, 0xbfb8aa3b, v5
	v_exp_f32_e32 v1, v0
	v_mul_f32_e32 v0, 0xbfb8aa3b, v8
	v_exp_f32_e32 v10, v0
	v_mul_f32_e32 v0, 0xbfb8aa3b, v9
	v_exp_f32_e32 v11, v0
	v_mul_f32_e32 v0, 0xbfb8aa3b, v6
	v_exp_f32_e32 v14, v0
	v_mul_f32_e32 v0, 0xbfb8aa3b, v7
	v_pk_add_f32 v[10:11], v[10:11], 1.0 op_sel_hi:[1,0]
	v_exp_f32_e32 v15, v0
	v_div_scale_f32 v13, s[2:3], v11, v11, v9
	v_rcp_f32_e32 v54, v13
	v_mul_f32_e32 v0, 0xbfb8aa3b, v2
	v_exp_f32_e32 v52, v0
	v_mul_f32_e32 v0, 0xbfb8aa3b, v3
	v_fma_f32 v55, -v13, v54, 1.0
	v_fmac_f32_e32 v54, v55, v54
	v_div_scale_f32 v55, vcc, v9, v11, v9
	v_mul_f32_e32 v56, v55, v54
	v_fma_f32 v57, -v13, v56, v55
	v_fmac_f32_e32 v56, v57, v54
	v_fma_f32 v13, -v13, v56, v55
	v_div_fmas_f32 v13, v13, v54, v56
	v_div_fixup_f32 v9, v13, v11, v9
	v_div_scale_f32 v11, s[2:3], v10, v10, v8
	v_rcp_f32_e32 v13, v11
	v_exp_f32_e32 v53, v0
	v_mul_f32_e32 v0, 0xbfb8aa3b, v4
	v_exp_f32_e32 v0, v0
	v_fma_f32 v54, -v11, v13, 1.0
	v_fmac_f32_e32 v13, v54, v13
	v_div_scale_f32 v54, vcc, v8, v10, v8
	v_mul_f32_e32 v55, v54, v13
	v_fma_f32 v56, -v11, v55, v54
	v_fmac_f32_e32 v55, v56, v13
	v_fma_f32 v11, -v11, v55, v54
	v_div_fmas_f32 v11, v11, v13, v55
	v_div_fixup_f32 v8, v11, v10, v8
	v_add_u32_e32 v10, 0x8900, v12
	ds_write2_b32 v10, v8, v9 offset1:1
	v_pk_add_f32 v[8:9], v[14:15], 1.0 op_sel_hi:[1,0]
	v_pk_add_f32 v[0:1], v[0:1], 1.0 op_sel_hi:[1,0]
	v_div_scale_f32 v10, s[2:3], v9, v9, v7
	v_rcp_f32_e32 v11, v10
	s_nop 0
	v_fma_f32 v13, -v10, v11, 1.0
	v_fmac_f32_e32 v11, v13, v11
	v_div_scale_f32 v13, vcc, v7, v9, v7
	v_mul_f32_e32 v14, v13, v11
	v_fma_f32 v15, -v10, v14, v13
	v_fmac_f32_e32 v14, v15, v11
	v_fma_f32 v10, -v10, v14, v13
	v_div_fmas_f32 v10, v10, v11, v14
	v_div_fixup_f32 v7, v10, v9, v7
	v_div_scale_f32 v9, s[2:3], v8, v8, v6
	v_rcp_f32_e32 v10, v9
	s_nop 0
	v_fma_f32 v11, -v9, v10, 1.0
	v_fmac_f32_e32 v10, v11, v10
	v_div_scale_f32 v11, vcc, v6, v8, v6
	v_mul_f32_e32 v13, v11, v10
	v_fma_f32 v14, -v9, v13, v11
	v_fmac_f32_e32 v13, v14, v10
	v_fma_f32 v9, -v9, v13, v11
	v_div_fmas_f32 v9, v9, v10, v13
	v_div_fixup_f32 v6, v9, v8, v6
	v_add_u32_e32 v8, 0x8908, v12
	ds_write2_b32 v8, v6, v7 offset1:1
	v_pk_add_f32 v[6:7], v[52:53], 1.0 op_sel_hi:[1,0]
	s_nop 0
	v_div_scale_f32 v8, s[2:3], v7, v7, v3
	v_rcp_f32_e32 v9, v8
	s_nop 0
	v_fma_f32 v10, -v8, v9, 1.0
	v_fmac_f32_e32 v9, v10, v9
	v_div_scale_f32 v10, vcc, v3, v7, v3
	v_mul_f32_e32 v11, v10, v9
	v_fma_f32 v13, -v8, v11, v10
	v_fmac_f32_e32 v11, v13, v9
	v_fma_f32 v8, -v8, v11, v10
	v_div_fmas_f32 v8, v8, v9, v11
	v_div_fixup_f32 v3, v8, v7, v3
	v_div_scale_f32 v7, s[2:3], v6, v6, v2
	v_rcp_f32_e32 v8, v7
	s_nop 0
	v_fma_f32 v9, -v7, v8, 1.0
	v_fmac_f32_e32 v8, v9, v8
	v_div_scale_f32 v9, vcc, v2, v6, v2
	v_mul_f32_e32 v10, v9, v8
	v_fma_f32 v11, -v7, v10, v9
	v_fmac_f32_e32 v10, v11, v8
	v_fma_f32 v7, -v7, v10, v9
	v_div_fmas_f32 v7, v7, v8, v10
	v_div_fixup_f32 v2, v7, v6, v2
	v_add_u32_e32 v6, 0x8910, v12
	ds_write2_b32 v6, v2, v3 offset1:1
	v_div_scale_f32 v2, s[2:3], v1, v1, v5
	v_rcp_f32_e32 v3, v2
	s_nop 0
	v_fma_f32 v6, -v2, v3, 1.0
	v_fmac_f32_e32 v3, v6, v3
	v_div_scale_f32 v6, vcc, v5, v1, v5
	v_mul_f32_e32 v7, v6, v3
	v_fma_f32 v8, -v2, v7, v6
	v_fmac_f32_e32 v7, v8, v3
	v_fma_f32 v2, -v2, v7, v6
	v_div_fmas_f32 v2, v2, v3, v7
	v_div_fixup_f32 v1, v2, v1, v5
	v_div_scale_f32 v2, s[2:3], v0, v0, v4
	v_rcp_f32_e32 v3, v2
	s_nop 0
	v_fma_f32 v5, -v2, v3, 1.0
	v_fmac_f32_e32 v3, v5, v3
	v_div_scale_f32 v5, vcc, v4, v0, v4
	v_mul_f32_e32 v6, v5, v3
	v_fma_f32 v7, -v2, v6, v5
	v_fmac_f32_e32 v6, v7, v3
	v_fma_f32 v2, -v2, v6, v5
	v_div_fmas_f32 v2, v2, v3, v6
	v_div_fixup_f32 v0, v2, v0, v4
	v_add_u32_e32 v2, 0x8918, v12
	v_cmp_gt_i32_e32 vcc, 0x80, v80
	ds_write2_b32 v2, v0, v1 offset1:1
	s_and_saveexec_b64 s[2:3], vcc
	s_cbranch_execz .LBB0_364
	s_ashr_i32 s4, s28, 5
	s_add_i32 s4, s4, s29
	s_mul_i32 s22, s22, -6
	s_ashr_i32 s5, s4, 31
	s_add_i32 s22, s54, s22
	s_ashr_i32 s6, s23, 31
	s_lshl_b64 s[4:5], s[4:5], 11
	s_add_u32 s4, s23, s4
	v_and_b32_e32 v4, 63, v80
	v_mov_b32_e32 v5, 0
	s_addc_u32 s5, s6, s5
	v_lshl_add_u64 v[0:1], s[4:5], 0, v[4:5]
	v_readlane_b32 s4, v252, 0
	v_readlane_b32 s5, v252, 1
	s_movk_i32 s6, 0xa00
	s_ashr_i32 s23, s22, 31
	v_mov_b64_e32 v[2:3], s[4:5]
	v_mad_u64_u32 v[2:3], s[4:5], v0, s6, v[2:3]
	v_mad_i32_i24 v3, v1, s6, v3
	v_lshrrev_b32_e32 v6, 6, v80
	v_mul_u32_u24_e32 v4, 12, v6
	v_lshl_add_u64 v[0:1], s[22:23], 1, v[2:3]
	s_lshl_b32 s34, s22, 2
	v_mov_b32_e32 v210, s34
	v_lshl_add_u64 v[0:1], v[0:1], 0, v[4:5]
	v_mad_u32_u24 v210, v6, 24, v210
	global_load_ushort v2, v[0:1], off offset:2304
	global_load_ushort v207, v[0:1], off offset:2328
	global_load_dword v209, v210, s[48:49]
	global_load_dword v211, v210, s[50:51]
	s_mov_b32 s9, 0xbfb8aa3b
	s_mov_b32 s10, 0x3f2aaaab
	s_mov_b32 s11, 0x3f317218
	s_mov_b32 s8, 0x7f800000
	s_mov_b32 s12, 0x33800000
	s_waitcnt vmcnt(0)
	v_lshlrev_b32_e32 v2, 16, v2
	v_mul_f32_e32 v2, 0xbfb8aa3b, v2
	v_exp_f32_e32 v2, v2
	s_nop 0
	v_add_f32_e32 v2, 1.0, v2
	v_div_scale_f32 v3, s[4:5], v2, v2, 1.0
	v_rcp_f32_e32 v4, v3
	s_nop 0
	v_fma_f32 v5, -v3, v4, 1.0
	v_fmac_f32_e32 v4, v5, v4
	v_div_scale_f32 v5, vcc, 1.0, v2, 1.0
	v_mul_f32_e32 v6, v5, v4
	v_fma_f32 v7, -v3, v6, v5
	v_fmac_f32_e32 v6, v7, v4
	v_fma_f32 v3, -v3, v6, v5
	v_div_fmas_f32 v3, v3, v4, v6
	v_div_fixup_f32 v3, v3, v2, 1.0
	v_lshl_add_u32 v2, v80, 2, 0
	v_add_u32_e32 v2, 0x21a00, v2
	ds_write_b32 v2, v3 offset:512
	v_mov_b32_e32 v4, v207
	v_mov_b32_e32 v3, v209
	v_mov_b32_e32 v5, v211
	v_lshlrev_b32_e32 v4, 16, v4
	v_mul_f32_e32 v3, 0x3fb8aa3b, v3
	v_add_f32_e32 v4, v5, v4
	v_max_f32_e32 v6, 0, v4
	v_mul_f32_e64 v4, |v4|, s9
	v_exp_f32_e32 v7, v4
	v_exp_f32_e32 v3, v3
	v_add_f32_e32 v8, 1.0, v7
	v_add_f32_e32 v4, -1.0, v8
	v_sub_f32_e32 v5, v4, v8
	v_add_f32_e32 v5, 1.0, v5
	v_sub_f32_e32 v4, v7, v4
	v_add_f32_e32 v9, v4, v5
	v_frexp_mant_f32_e32 v4, v8
	v_cmp_gt_f32_e32 vcc, s10, v4
	v_cvt_f64_f32_e32 v[4:5], v8
	v_frexp_exp_i32_f64_e32 v4, v[4:5]
	v_subbrev_co_u32_e32 v4, vcc, 0, v4, vcc
	v_sub_u32_e32 v5, 0, v4
	v_ldexp_f32 v8, v8, v5
	v_ldexp_f32 v5, v9, v5
	v_add_f32_e32 v9, -1.0, v8
	v_add_f32_e32 v10, 1.0, v9
	v_sub_f32_e32 v10, v8, v10
	v_add_f32_e32 v10, v5, v10
	v_add_f32_e32 v11, v9, v10
	v_sub_f32_e32 v9, v11, v9
	v_sub_f32_e32 v9, v10, v9
	v_add_f32_e32 v10, 1.0, v8
	v_add_f32_e32 v12, -1.0, v10
	v_sub_f32_e32 v8, v8, v12
	v_add_f32_e32 v5, v5, v8
	v_add_f32_e32 v8, v10, v5
	v_sub_f32_e32 v10, v8, v10
	v_sub_f32_e32 v5, v5, v10
	v_rcp_f32_e32 v10, v8
	v_cvt_f32_i32_e32 v4, v4
	v_cmp_neq_f32_e32 vcc, s8, v7
	v_mul_f32_e32 v12, v11, v10
	v_mul_f32_e32 v13, v8, v12
	v_fma_f32 v14, v12, v8, -v13
	v_fmac_f32_e32 v14, v12, v5
	v_add_f32_e32 v15, v13, v14
	v_sub_f32_e32 v52, v11, v15
	v_sub_f32_e32 v11, v11, v52
	v_sub_f32_e32 v13, v15, v13
	v_sub_f32_e32 v11, v11, v15
	v_add_f32_e32 v9, v9, v11
	v_sub_f32_e32 v11, v13, v14
	v_add_f32_e32 v9, v11, v9
	v_add_f32_e32 v11, v52, v9
	v_mul_f32_e32 v13, v10, v11
	v_mul_f32_e32 v14, v8, v13
	v_fma_f32 v8, v13, v8, -v14
	v_fmac_f32_e32 v8, v13, v5
	v_sub_f32_e32 v5, v52, v11
	v_add_f32_e32 v5, v9, v5
	v_add_f32_e32 v9, v14, v8
	v_sub_f32_e32 v15, v11, v9
	v_sub_f32_e32 v11, v11, v15
	v_sub_f32_e32 v14, v9, v14
	v_sub_f32_e32 v9, v11, v9
	v_add_f32_e32 v5, v5, v9
	v_sub_f32_e32 v8, v14, v8
	v_add_f32_e32 v5, v8, v5
	v_add_f32_e32 v8, v12, v13
	v_add_f32_e32 v5, v15, v5
	v_sub_f32_e32 v9, v8, v12
	v_mul_f32_e32 v5, v10, v5
	v_sub_f32_e32 v9, v13, v9
	v_add_f32_e32 v5, v9, v5
	v_mul_f32_e32 v12, 0x3f317218, v4
	v_add_f32_e32 v9, v8, v5
	v_fma_f32 v13, v4, s11, -v12
	v_mul_f32_e32 v10, v9, v9
	v_fmac_f32_e32 v13, 0xb102e308, v4
	v_sub_f32_e32 v4, v9, v8
	v_fmamk_f32 v11, v10, 0x3e9b6dac, v237
	v_sub_f32_e32 v4, v5, v4
	v_add_f32_e32 v5, v12, v13
	v_fmaak_f32 v11, v10, v11, 0x3f2aaada
	v_sub_f32_e32 v8, v5, v12
	v_ldexp_f32 v12, v9, 1
	v_mul_f32_e32 v9, v9, v10
	v_mul_f32_e32 v9, v9, v11
	v_add_f32_e32 v10, v12, v9
	v_sub_f32_e32 v11, v10, v12
	v_ldexp_f32 v4, v4, 1
	v_sub_f32_e32 v9, v9, v11
	v_add_f32_e32 v4, v4, v9
	v_add_f32_e32 v9, v10, v4
	v_sub_f32_e32 v10, v9, v10
	v_sub_f32_e32 v4, v4, v10
	v_add_f32_e32 v10, v5, v9
	v_sub_f32_e32 v11, v10, v5
	v_sub_f32_e32 v12, v10, v11
	v_sub_f32_e32 v8, v13, v8
	v_sub_f32_e32 v5, v5, v12
	v_sub_f32_e32 v9, v9, v11
	v_add_f32_e32 v5, v9, v5
	v_add_f32_e32 v9, v8, v4
	v_sub_f32_e32 v11, v9, v8
	v_sub_f32_e32 v12, v9, v11
	v_sub_f32_e32 v8, v8, v12
	v_sub_f32_e32 v4, v4, v11
	v_add_f32_e32 v5, v9, v5
	v_add_f32_e32 v4, v4, v8
	v_add_f32_e32 v8, v10, v5
	v_sub_f32_e32 v9, v8, v10
	v_sub_f32_e32 v5, v5, v9
	v_add_f32_e32 v4, v4, v5
	v_add_f32_e32 v4, v8, v4
	v_cndmask_b32_e32 v4, v239, v4, vcc
	v_cmp_ngt_f32_e32 vcc, -1.0, v7
	s_nop 1
	v_cndmask_b32_e32 v4, v238, v4, vcc
	v_cmp_neq_f32_e32 vcc, -1.0, v7
	s_nop 1
	v_cndmask_b32_e32 v4, v243, v4, vcc
	v_cmp_lt_f32_e64 vcc, |v7|, s12
	s_nop 1
	v_cndmask_b32_e32 v4, v4, v7, vcc
	v_add_f32_e32 v4, v6, v4
	v_mul_f32_e64 v3, v4, -v3
	ds_write_b32 v2, v3
